# P1 phase entry: workgroups delayed by (blockIdx&3)*~15us with s_sleep so the XCDs' epilogue store bursts are spread in time
# speedup vs baseline: 1.0012x; 1.0012x over previous
; __global__ void __launch_bounds__(NTHREADS, 2) enc_fwd(Args args) {
;     ...
;     if (IN(1)) {
;     ...
; #pragma unroll 1
;         for (int rep = 0; rep < REP1A; ++rep)
;         { OpsP1 O{(const char*)F.XB, (const char*)F.WinT16}; pg8::StaticOrder S; S.init(M, N16, F.G, F.bx, 1);
;           pg8::EpiH16 E{F.U, F.V, F.ZA, F.VSTAT};
;           pg8::gemm_phase<pg8::EpiH16, pg8::StaticOrder, OpsP1, true, true, 0>(F.lds, O, S, E, F.wave); }
.LBB0_112:
	s_and_b32 s98, s2, 3
	s_mul_i32 s98, s98, 60
.Lstag0_loop:
	s_cmp_eq_u32 s98, 0
	s_cbranch_scc1 .Lstag0_done
	s_sleep 8
	s_sub_u32 s98, s98, 1
	s_branch .Lstag0_loop

; #define PG8_STAGE(bufoff, rsrc, soff, voff) do { _Pragma("unroll") for (int _i = 0; _i < 2; ++_i) \
;         __builtin_amdgcn_raw_ptr_buffer_load_lds(rsrc, (LAS void*)(lds + (bufoff) + ldsw + _i * 8192), 16, (int)(voff)[0], (int)((soff) + (unsigned)_i * (64u * K * 2u)), 0, 0); } while (0)
; #define PG8_WAIT_V(n) asm volatile("s_waitcnt vmcnt(" #n ")" ::: "memory")
; #define PG8_BAR __builtin_amdgcn_s_barrier()
;     ...
;         PG8_STAGE(PG8_SB(0, 0), rB, cB, voffB); PG8_STAGE(PG8_SB(0, 1), rB, cB + hstep, voffB); PG8_STAGE(PG8_SA(0, 0), rA, cA, voffA); PG8_STAGE(PG8_SA(0, 1), rA, cA + hstep, voffA);
;         if (wr == 1) PG8_BAR;
;         PG8_WAIT_V(2); PG8_BAR;
;         PG8_STAGE(PG8_SB(1, 0), rB, cB + kstep, voffB); PG8_STAGE(PG8_SA(1, 0), rA, cA + kstep, voffA); PG8_STAGE(PG8_SB(1, 1), rB, cB + hstep + kstep, voffB);
;         PG8_WAIT_V(6); PG8_BAR;
;     } else {
;         PG8_STAGE(PG8_SB(0, 0), rB, cB, voffB); PG8_STAGE(PG8_SA(0, 0), rA, cA, voffA); PG8_STAGE(PG8_SB(0, 1), rB, cB + hstep, voffB); PG8_STAGE(PG8_SA(0, 1), rA, cA + hstep, voffA);
;         if (wr == 1) PG8_BAR;
;         PG8_WAIT_V(4); PG8_BAR;
;         PG8_STAGE(PG8_SB(1, 0), rB, cB + kstep, voffB); PG8_STAGE(PG8_SA(1, 0), rA, cA + kstep, voffA); PG8_STAGE(PG8_SB(1, 1), rB, cB + hstep + kstep, voffB);
;         PG8_WAIT_V(6); PG8_BAR;
.LBB0_507:
	s_add_i32 s53, s3, 0x18000
	s_or_b32 s21, s75, 0x80
	s_mov_b32 s30, s18
	s_mov_b32 s31, s19
	s_mov_b32 m0, s53
	s_add_i32 s54, s3, 0x1a000
	s_waitcnt vmcnt(2)
	s_barrier
	buffer_load_dwordx4 v133, s[28:31], s21 offen lds
	s_or_b32 s21, s75, 0x80080
	s_mov_b32 m0, s54
	s_add_i32 s55, s3, 0x8000
	buffer_load_dwordx4 v133, s[28:31], s21 offen lds
	s_or_b32 s21, s73, 0x80
	s_mov_b32 m0, s55
	s_add_i32 s56, s3, 0xa000
	buffer_load_dwordx4 v132, s[16:19], s21 offen lds
	s_or_b32 s21, s73, 0x80080
	s_mov_b32 m0, s56
	s_add_i32 s57, s3, 0x1c000
	buffer_load_dwordx4 v132, s[16:19], s21 offen lds
	s_or_b32 s21, s75, 0x100080
	s_mov_b32 m0, s57
	s_add_i32 s58, s3, 0x1e000
	buffer_load_dwordx4 v133, s[28:31], s21 offen lds
	s_or_b32 s21, s75, 0x180080
	s_mov_b32 m0, s58
	s_lshl_b32 s20, s20, 5
	buffer_load_dwordx4 v133, s[28:31], s21 offen lds
	v_and_b32_e32 v2, 15, v0
	v_lshlrev_b32_e32 v1, 4, v1
	v_and_b32_e32 v0, 48, v0
	s_and_b32 s20, s20, 0x60
	s_lshl_b32 s5, s5, 13
	v_lshlrev_b32_e32 v3, 7, v2
	v_or_b32_e32 v2, s20, v2
	v_xad_u32 v0, v1, v0, 0
	s_waitcnt vmcnt(6)
	s_add_i32 s59, s3, 0xc000
	v_add3_u32 v134, v0, s5, v3
	v_lshl_add_u32 v0, v2, 7, v0
	v_mov_b32_e32 v1, 0x10000
	s_cmpk_lt_u32 s4, 0x100
	v_xad_u32 v135, v0, 64, v1
	v_add_u32_e32 v136, 0x10000, v0
	v_add_u32_e32 v137, 0x14000, v0
	v_xor_b32_e32 v138, 64, v134
	v_add_u32_e32 v139, 0x18000, v0
	s_waitcnt lgkmcnt(1)
	v_add_u32_e32 v140, 0x1c000, v0
	s_cselect_b64 s[20:21], -1, 0
	s_waitcnt lgkmcnt(0)
	v_add_u32_e32 v141, 0x10800, v0
	v_add_u32_e32 v142, 0x14800, v0
	s_add_i32 s60, s3, 0xe000
	v_add_u32_e32 v143, 0x18800, v0
	v_add_u32_e32 v144, 0x1c800, v0
	s_ashr_i32 s61, s34, 31
	v_mov_b64_e32 v[128:129], 0x600
	v_mov_b64_e32 v[130:131], 0x5ff
	s_mov_b64 s[22:23], 0x100000
	s_mov_b64 s[24:25], 0x120000
	s_mov_b32 s62, 0x120000
	s_mov_b64 s[44:45], 0x140000
	s_mov_b32 s63, 0x140000
	s_mov_b64 s[46:47], 0x160000
	s_mov_b32 s64, 0x160000
	s_barrier
	s_branch .LBB0_510

; #define PG8_STAGE(bufoff, rsrc, soff, voff) do { _Pragma("unroll") for (int _i = 0; _i < 2; ++_i) \
;         __builtin_amdgcn_raw_ptr_buffer_load_lds(rsrc, (LAS void*)(lds + (bufoff) + ldsw + _i * 8192), 16, (int)(voff)[0], (int)((soff) + (unsigned)_i * (64u * K * 2u)), 0, 0); } while (0)
; #define PG8_WAIT_VN(n) asm volatile("s_waitcnt vmcnt(%0)" :: "n"(n) : "memory")
; #define PG8_WAIT_V(n) asm volatile("s_waitcnt vmcnt(" #n ")" ::: "memory")
; #define PG8_WAIT_L(n) asm volatile("s_waitcnt lgkmcnt(" #n ")" ::: "memory")
; #define PG8_BAR __builtin_amdgcn_s_barrier()
; #define PG8_SCHED __builtin_amdgcn_sched_barrier(0)
;     ...
;             PG8_LDB(B0, 0, 0); PG8_LDB(B1, 0, 1); PG8_SCHED; PG8_LDA(At, 0, 0); PG8_STAGE(PG8_SA(1, 1), rA, a1 + hstep, voffA);
;             if (relax) PG8_WAIT_VN(VRELAX); else PG8_WAIT_V(8); PG8_WAIT_L(0); PG8_BAR; PG8_MMA(0, 0, At, B0); PG8_MMA(0, 1, At, B1); PG8_BAR; PG8_SCHED;
;             PG8_LDA(At, 0, 1); PG8_STAGE(PG8_SB(0, 0), rB, b2, voffB); PG8_STAGE(PG8_SB(0, 1), rB, b2 + hstep, voffB); PG8_STAGE(PG8_SA(0, 0), rA, a2, voffA);
;             if (relax) PG8_WAIT_VN(VRELAX); else PG8_WAIT_V(8); PG8_WAIT_L(0); PG8_BAR; PG8_MMA(1, 0, At, B0); PG8_MMA(1, 1, At, B1); PG8_BAR; PG8_SCHED;
.LBB0_513:
	v_mov_b32_e32 v145, v135
	ds_read_b128 v[146:149], v136
	ds_read_b128 v[150:153], v141
	ds_read_b128 v[154:157], v145
	ds_read_b128 v[158:161], v145 offset:2048
	v_mov_b32_e32 v145, v135
	ds_read_b128 v[162:165], v137
	ds_read_b128 v[166:169], v142
	ds_read_b128 v[170:173], v145 offset:16384
	ds_read_b128 v[174:177], v145 offset:18432
	s_add_i32 s30, s73, 0xffe80080
	s_cmp_eq_u32 s76, 60
	s_cselect_b32 s77, s71, s30
	s_cselect_b32 s79, s72, s75
	s_or_b32 s78, s77, 0x80
	v_mov_b32_e32 v145, v138
	s_add_i32 s30, s73, 0xfff80000
	s_mov_b32 m0, s59
	ds_read_b128 v[178:181], v134
	ds_read_b128 v[182:185], v134 offset:2048
	ds_read_b128 v[186:189], v145
	ds_read_b128 v[190:193], v145 offset:2048
	ds_read_b128 v[194:197], v134 offset:4096
	ds_read_b128 v[198:201], v134 offset:6144
	ds_read_b128 v[202:205], v145 offset:4096
	ds_read_b128 v[206:209], v145 offset:6144
	buffer_load_dwordx4 v132, s[16:19], s30 offen lds
	s_mov_b32 m0, s60
	s_nop 0
	buffer_load_dwordx4 v132, s[16:19], s73 offen lds
	s_waitcnt vmcnt(8)
	s_waitcnt lgkmcnt(0)
	s_barrier
	s_setprio 1
	s_waitcnt lgkmcnt(7)
	v_mfma_f32_16x16x32_bf16 v[124:127], v[146:149], v[178:181], v[124:127]
	v_mfma_f32_16x16x32_bf16 v[120:123], v[150:153], v[178:181], v[120:123]
	s_waitcnt lgkmcnt(6)
	v_mfma_f32_16x16x32_bf16 v[116:119], v[146:149], v[182:185], v[116:119]
	v_mfma_f32_16x16x32_bf16 v[108:111], v[150:153], v[182:185], v[108:111]
	s_waitcnt lgkmcnt(3)
	v_mfma_f32_16x16x32_bf16 v[100:103], v[146:149], v[194:197], v[100:103]
	v_mfma_f32_16x16x32_bf16 v[92:95], v[150:153], v[194:197], v[92:95]
	s_waitcnt lgkmcnt(2)
	v_mfma_f32_16x16x32_bf16 v[84:87], v[146:149], v[198:201], v[84:87]
	v_mfma_f32_16x16x32_bf16 v[76:79], v[150:153], v[198:201], v[76:79]
	v_mfma_f32_16x16x32_bf16 v[124:127], v[154:157], v[186:189], v[124:127]
	v_mfma_f32_16x16x32_bf16 v[120:123], v[158:161], v[186:189], v[120:123]
	v_mfma_f32_16x16x32_bf16 v[116:119], v[154:157], v[190:193], v[116:119]
	v_mfma_f32_16x16x32_bf16 v[108:111], v[158:161], v[190:193], v[108:111]
	s_waitcnt lgkmcnt(1)
	v_mfma_f32_16x16x32_bf16 v[100:103], v[154:157], v[202:205], v[100:103]
	v_mfma_f32_16x16x32_bf16 v[92:95], v[158:161], v[202:205], v[92:95]
	s_waitcnt lgkmcnt(0)
	v_mfma_f32_16x16x32_bf16 v[84:87], v[154:157], v[206:209], v[84:87]
	v_mfma_f32_16x16x32_bf16 v[76:79], v[158:161], v[206:209], v[76:79]
	s_setprio 0
	s_setprio 1
	v_mfma_f32_16x16x32_bf16 v[112:115], v[162:165], v[178:181], v[112:115]
	v_mfma_f32_16x16x32_bf16 v[104:107], v[166:169], v[178:181], v[104:107]
	v_mfma_f32_16x16x32_bf16 v[96:99], v[162:165], v[182:185], v[96:99]
	v_mfma_f32_16x16x32_bf16 v[88:91], v[166:169], v[182:185], v[88:91]
	v_mfma_f32_16x16x32_bf16 v[80:83], v[162:165], v[194:197], v[80:83]
	v_mfma_f32_16x16x32_bf16 v[72:75], v[166:169], v[194:197], v[72:75]
	v_mfma_f32_16x16x32_bf16 v[68:71], v[162:165], v[198:201], v[68:71]
	v_mfma_f32_16x16x32_bf16 v[64:67], v[166:169], v[198:201], v[64:67]
	v_mfma_f32_16x16x32_bf16 v[112:115], v[170:173], v[186:189], v[112:115]
	v_mfma_f32_16x16x32_bf16 v[104:107], v[174:177], v[186:189], v[104:107]
	v_mfma_f32_16x16x32_bf16 v[96:99], v[170:173], v[190:193], v[96:99]
	v_mfma_f32_16x16x32_bf16 v[88:91], v[174:177], v[190:193], v[88:91]
	v_mfma_f32_16x16x32_bf16 v[80:83], v[170:173], v[202:205], v[80:83]
	v_mfma_f32_16x16x32_bf16 v[72:75], v[174:177], v[202:205], v[72:75]
	v_mfma_f32_16x16x32_bf16 v[68:71], v[170:173], v[206:209], v[68:71]
	v_mfma_f32_16x16x32_bf16 v[64:67], v[174:177], v[206:209], v[64:67]
	s_setprio 0
	s_barrier
	s_mov_b32 m0, s10
	v_mov_b32_e32 v145, v138
	s_mov_b32 s30, s18
	s_mov_b32 s31, s19
	ds_read_b128 v[178:181], v134 offset:16384
	ds_read_b128 v[182:185], v134 offset:18432
	ds_read_b128 v[186:189], v145 offset:16384
	ds_read_b128 v[190:193], v145 offset:18432
	ds_read_b128 v[194:197], v134 offset:20480
	ds_read_b128 v[198:201], v134 offset:22528
	ds_read_b128 v[202:205], v145 offset:20480
	ds_read_b128 v[206:209], v145 offset:22528
	buffer_load_dwordx4 v133, s[28:31], s79 offen lds
	s_add_i32 s80, s79, 0x80000
	s_mov_b32 m0, s11
	s_nop 0
	buffer_load_dwordx4 v133, s[28:31], s80 offen lds
	s_add_i32 s80, s79, 0x100000
	s_mov_b32 m0, s33
	s_nop 0
	buffer_load_dwordx4 v133, s[28:31], s80 offen lds
	s_add_i32 s80, s79, 0x180000
	s_mov_b32 m0, s35
	s_nop 0
	buffer_load_dwordx4 v133, s[28:31], s80 offen lds
	s_mov_b32 m0, s3
	s_add_i32 s80, s77, 0x80000
	buffer_load_dwordx4 v132, s[16:19], s77 offen lds
	s_mov_b32 m0, s48
	s_nop 0
	buffer_load_dwordx4 v132, s[16:19], s80 offen lds
	s_waitcnt vmcnt(8)
	s_waitcnt lgkmcnt(0)
	s_barrier
; #define PG8_STAGE(bufoff, rsrc, soff, voff) do { _Pragma("unroll") for (int _i = 0; _i < 2; ++_i) \
;         __builtin_amdgcn_raw_ptr_buffer_load_lds(rsrc, (LAS void*)(lds + (bufoff) + ldsw + _i * 8192), 16, (int)(voff)[0], (int)((soff) + (unsigned)_i * (64u * K * 2u)), 0, 0); } while (0)
; #define PG8_WAIT_VN(n) asm volatile("s_waitcnt vmcnt(%0)" :: "n"(n) : "memory")
; #define PG8_WAIT_V(n) asm volatile("s_waitcnt vmcnt(" #n ")" ::: "memory")
; #define PG8_WAIT_L(n) asm volatile("s_waitcnt lgkmcnt(" #n ")" ::: "memory")
; #define PG8_BAR __builtin_amdgcn_s_barrier()
; #define PG8_SCHED __builtin_amdgcn_sched_barrier(0)
;     ...
;             if (relax) PG8_WAIT_VN(VRELAX); else PG8_WAIT_V(8); PG8_WAIT_L(0); PG8_BAR; PG8_MMA(1, 0, At, B0); PG8_MMA(1, 1, At, B1); PG8_BAR; PG8_SCHED;
;             PG8_LDB(B0, 1, 0); PG8_LDB(B1, 1, 1); PG8_SCHED; PG8_LDA(At, 1, 0); PG8_STAGE(PG8_SA(0, 1), rA, a2 + hstep, voffA);
;             PG8_WAIT_V(8); PG8_WAIT_L(0); PG8_BAR; PG8_MMA(0, 0, At, B0); PG8_MMA(0, 1, At, B1); PG8_BAR; PG8_SCHED;
	s_setprio 1
	s_waitcnt lgkmcnt(7)
	v_mfma_f32_16x16x32_bf16 v[60:63], v[146:149], v[178:181], v[60:63]
	v_mfma_f32_16x16x32_bf16 v[56:59], v[150:153], v[178:181], v[56:59]
	s_waitcnt lgkmcnt(6)
	v_mfma_f32_16x16x32_bf16 v[52:55], v[146:149], v[182:185], v[52:55]
	v_mfma_f32_16x16x32_bf16 v[48:51], v[150:153], v[182:185], v[48:51]
	s_waitcnt lgkmcnt(3)
	v_mfma_f32_16x16x32_bf16 v[36:39], v[146:149], v[194:197], v[36:39]
	v_mfma_f32_16x16x32_bf16 v[32:35], v[150:153], v[194:197], v[32:35]
	s_waitcnt lgkmcnt(2)
	v_mfma_f32_16x16x32_bf16 v[20:23], v[146:149], v[198:201], v[20:23]
	v_mfma_f32_16x16x32_bf16 v[16:19], v[150:153], v[198:201], v[16:19]
	v_mfma_f32_16x16x32_bf16 v[60:63], v[154:157], v[186:189], v[60:63]
	v_mfma_f32_16x16x32_bf16 v[56:59], v[158:161], v[186:189], v[56:59]
	v_mfma_f32_16x16x32_bf16 v[52:55], v[154:157], v[190:193], v[52:55]
	v_mfma_f32_16x16x32_bf16 v[48:51], v[158:161], v[190:193], v[48:51]
	s_waitcnt lgkmcnt(1)
	v_mfma_f32_16x16x32_bf16 v[36:39], v[154:157], v[202:205], v[36:39]
	v_mfma_f32_16x16x32_bf16 v[32:35], v[158:161], v[202:205], v[32:35]
	s_waitcnt lgkmcnt(0)
	v_mfma_f32_16x16x32_bf16 v[20:23], v[154:157], v[206:209], v[20:23]
	v_mfma_f32_16x16x32_bf16 v[16:19], v[158:161], v[206:209], v[16:19]
	s_setprio 0
	s_setprio 1
	v_mfma_f32_16x16x32_bf16 v[44:47], v[162:165], v[178:181], v[44:47]
	v_mfma_f32_16x16x32_bf16 v[40:43], v[166:169], v[178:181], v[40:43]
	v_mfma_f32_16x16x32_bf16 v[28:31], v[162:165], v[182:185], v[28:31]
	v_mfma_f32_16x16x32_bf16 v[24:27], v[166:169], v[182:185], v[24:27]
	v_mfma_f32_16x16x32_bf16 v[12:15], v[162:165], v[194:197], v[12:15]
	v_mfma_f32_16x16x32_bf16 v[8:11], v[166:169], v[194:197], v[8:11]
	v_mfma_f32_16x16x32_bf16 v[4:7], v[162:165], v[198:201], v[4:7]
	v_mfma_f32_16x16x32_bf16 v[0:3], v[166:169], v[198:201], v[0:3]
	v_mfma_f32_16x16x32_bf16 v[44:47], v[170:173], v[186:189], v[44:47]
	v_mfma_f32_16x16x32_bf16 v[40:43], v[174:177], v[186:189], v[40:43]
	v_mfma_f32_16x16x32_bf16 v[28:31], v[170:173], v[190:193], v[28:31]
	v_mfma_f32_16x16x32_bf16 v[24:27], v[174:177], v[190:193], v[24:27]
	v_mfma_f32_16x16x32_bf16 v[12:15], v[170:173], v[202:205], v[12:15]
	v_mfma_f32_16x16x32_bf16 v[8:11], v[174:177], v[202:205], v[8:11]
	v_mfma_f32_16x16x32_bf16 v[4:7], v[170:173], v[206:209], v[4:7]
	v_mfma_f32_16x16x32_bf16 v[0:3], v[174:177], v[206:209], v[0:3]
	s_setprio 0
	s_barrier
	v_mov_b32_e32 v145, v135
	ds_read_b128 v[146:149], v139
	ds_read_b128 v[150:153], v143
	ds_read_b128 v[154:157], v145 offset:32768
	ds_read_b128 v[158:161], v145 offset:34816
	v_mov_b32_e32 v145, v135
	ds_read_b128 v[162:165], v140
	ds_read_b128 v[166:169], v144
	ds_read_b128 v[170:173], v145 offset:49152
	ds_read_b128 v[174:177], v145 offset:51200
	s_mov_b32 m0, s49
	v_mov_b32_e32 v145, v138
	s_add_i32 s80, s77, 0x100000
	ds_read_b128 v[178:181], v134 offset:32768
	ds_read_b128 v[182:185], v134 offset:34816
	ds_read_b128 v[186:189], v145 offset:32768
	ds_read_b128 v[190:193], v145 offset:34816
	ds_read_b128 v[194:197], v134 offset:36864
	ds_read_b128 v[198:201], v134 offset:38912
	ds_read_b128 v[202:205], v145 offset:36864
	ds_read_b128 v[206:209], v145 offset:38912
	buffer_load_dwordx4 v132, s[16:19], s80 offen lds
	s_add_i32 s80, s77, 0x180000
	s_mov_b32 m0, s50
	s_nop 0
	buffer_load_dwordx4 v132, s[16:19], s80 offen lds
	s_waitcnt vmcnt(8)
	s_waitcnt lgkmcnt(0)
	s_barrier
	s_setprio 1
	s_waitcnt lgkmcnt(7)
	v_mfma_f32_16x16x32_bf16 v[124:127], v[146:149], v[178:181], v[124:127]
	v_mfma_f32_16x16x32_bf16 v[120:123], v[150:153], v[178:181], v[120:123]
	s_waitcnt lgkmcnt(6)
	v_mfma_f32_16x16x32_bf16 v[116:119], v[146:149], v[182:185], v[116:119]
	v_mfma_f32_16x16x32_bf16 v[108:111], v[150:153], v[182:185], v[108:111]
	s_waitcnt lgkmcnt(3)
	v_mfma_f32_16x16x32_bf16 v[100:103], v[146:149], v[194:197], v[100:103]
	v_mfma_f32_16x16x32_bf16 v[92:95], v[150:153], v[194:197], v[92:95]
	s_waitcnt lgkmcnt(2)
	v_mfma_f32_16x16x32_bf16 v[84:87], v[146:149], v[198:201], v[84:87]
	v_mfma_f32_16x16x32_bf16 v[76:79], v[150:153], v[198:201], v[76:79]
	v_mfma_f32_16x16x32_bf16 v[124:127], v[154:157], v[186:189], v[124:127]
	v_mfma_f32_16x16x32_bf16 v[120:123], v[158:161], v[186:189], v[120:123]
	v_mfma_f32_16x16x32_bf16 v[116:119], v[154:157], v[190:193], v[116:119]
	v_mfma_f32_16x16x32_bf16 v[108:111], v[158:161], v[190:193], v[108:111]
	s_waitcnt lgkmcnt(1)
	v_mfma_f32_16x16x32_bf16 v[100:103], v[154:157], v[202:205], v[100:103]
	v_mfma_f32_16x16x32_bf16 v[92:95], v[158:161], v[202:205], v[92:95]
	s_waitcnt lgkmcnt(0)
	v_mfma_f32_16x16x32_bf16 v[84:87], v[154:157], v[206:209], v[84:87]
	v_mfma_f32_16x16x32_bf16 v[76:79], v[158:161], v[206:209], v[76:79]
	s_setprio 0
	s_setprio 1
	v_mfma_f32_16x16x32_bf16 v[112:115], v[162:165], v[178:181], v[112:115]
	v_mfma_f32_16x16x32_bf16 v[104:107], v[166:169], v[178:181], v[104:107]
	v_mfma_f32_16x16x32_bf16 v[96:99], v[162:165], v[182:185], v[96:99]
	v_mfma_f32_16x16x32_bf16 v[88:91], v[166:169], v[182:185], v[88:91]
	v_mfma_f32_16x16x32_bf16 v[80:83], v[162:165], v[194:197], v[80:83]
	v_mfma_f32_16x16x32_bf16 v[72:75], v[166:169], v[194:197], v[72:75]
	v_mfma_f32_16x16x32_bf16 v[68:71], v[162:165], v[198:201], v[68:71]
	v_mfma_f32_16x16x32_bf16 v[64:67], v[166:169], v[198:201], v[64:67]
	v_mfma_f32_16x16x32_bf16 v[112:115], v[170:173], v[186:189], v[112:115]
	v_mfma_f32_16x16x32_bf16 v[104:107], v[174:177], v[186:189], v[104:107]
	v_mfma_f32_16x16x32_bf16 v[96:99], v[170:173], v[190:193], v[96:99]
	v_mfma_f32_16x16x32_bf16 v[88:91], v[174:177], v[190:193], v[88:91]
	v_mfma_f32_16x16x32_bf16 v[80:83], v[170:173], v[202:205], v[80:83]
	v_mfma_f32_16x16x32_bf16 v[72:75], v[174:177], v[202:205], v[72:75]
	v_mfma_f32_16x16x32_bf16 v[68:71], v[170:173], v[206:209], v[68:71]
	v_mfma_f32_16x16x32_bf16 v[64:67], v[174:177], v[206:209], v[64:67]
	s_setprio 0
	s_barrier
; #define PG8_STAGE(bufoff, rsrc, soff, voff) do { _Pragma("unroll") for (int _i = 0; _i < 2; ++_i) \
;         __builtin_amdgcn_raw_ptr_buffer_load_lds(rsrc, (LAS void*)(lds + (bufoff) + ldsw + _i * 8192), 16, (int)(voff)[0], (int)((soff) + (unsigned)_i * (64u * K * 2u)), 0, 0); } while (0)
; #define PG8_WAIT_V(n) asm volatile("s_waitcnt vmcnt(" #n ")" ::: "memory")
; #define PG8_WAIT_L(n) asm volatile("s_waitcnt lgkmcnt(" #n ")" ::: "memory")
; #define PG8_BAR __builtin_amdgcn_s_barrier()
; #define PG8_SCHED __builtin_amdgcn_sched_barrier(0)
;     ...
;             PG8_LDB(B0, 1, 0); PG8_LDB(B1, 1, 1); PG8_SCHED; PG8_LDA(At, 1, 0); PG8_STAGE(PG8_SA(0, 1), rA, a2 + hstep, voffA);
;             PG8_WAIT_V(8); PG8_WAIT_L(0); PG8_BAR; PG8_MMA(0, 0, At, B0); PG8_MMA(0, 1, At, B1); PG8_BAR; PG8_SCHED;
;             PG8_LDA(At, 1, 1); PG8_STAGE(PG8_SB(1, 0), rB, b3, voffB); PG8_STAGE(PG8_SB(1, 1), rB, b3 + hstep, voffB); PG8_STAGE(PG8_SA(1, 0), rA, a3, voffA);
;             PG8_WAIT_V(8); PG8_WAIT_L(0); PG8_BAR; PG8_MMA(1, 0, At, B0); PG8_MMA(1, 1, At, B1); PG8_BAR; PG8_SCHED;
	s_mov_b32 m0, s53
	v_mov_b32_e32 v145, v138
	s_or_b32 s80, s79, 0x80
	ds_read_b128 v[178:181], v134 offset:49152
	ds_read_b128 v[182:185], v134 offset:51200
	ds_read_b128 v[186:189], v145 offset:49152
	ds_read_b128 v[190:193], v145 offset:51200
	ds_read_b128 v[194:197], v134 offset:53248
	ds_read_b128 v[198:201], v134 offset:55296
	ds_read_b128 v[202:205], v145 offset:53248
	ds_read_b128 v[206:209], v145 offset:55296
	buffer_load_dwordx4 v133, s[28:31], s80 offen lds
	s_add_i32 s80, s79, 0x80080
	s_mov_b32 m0, s54
	s_add_i32 s77, s77, 0x80080
	buffer_load_dwordx4 v133, s[28:31], s80 offen lds
	s_add_i32 s80, s79, 0x100080
	s_mov_b32 m0, s57
	s_add_i32 s79, s79, 0x180080
	buffer_load_dwordx4 v133, s[28:31], s80 offen lds
	s_mov_b32 m0, s58
	s_nop 0
	buffer_load_dwordx4 v133, s[28:31], s79 offen lds
	s_mov_b32 m0, s55
	s_nop 0
	buffer_load_dwordx4 v132, s[16:19], s78 offen lds
	s_mov_b32 m0, s56
	s_nop 0
	buffer_load_dwordx4 v132, s[16:19], s77 offen lds
	s_waitcnt vmcnt(8)
	s_waitcnt lgkmcnt(0)
	s_barrier
	s_setprio 1
	s_waitcnt lgkmcnt(7)
	v_mfma_f32_16x16x32_bf16 v[60:63], v[146:149], v[178:181], v[60:63]
	v_mfma_f32_16x16x32_bf16 v[56:59], v[150:153], v[178:181], v[56:59]
	s_waitcnt lgkmcnt(6)
	v_mfma_f32_16x16x32_bf16 v[52:55], v[146:149], v[182:185], v[52:55]
	v_mfma_f32_16x16x32_bf16 v[48:51], v[150:153], v[182:185], v[48:51]
	s_waitcnt lgkmcnt(3)
	v_mfma_f32_16x16x32_bf16 v[36:39], v[146:149], v[194:197], v[36:39]
	v_mfma_f32_16x16x32_bf16 v[32:35], v[150:153], v[194:197], v[32:35]
	s_waitcnt lgkmcnt(2)
	v_mfma_f32_16x16x32_bf16 v[20:23], v[146:149], v[198:201], v[20:23]
	v_mfma_f32_16x16x32_bf16 v[16:19], v[150:153], v[198:201], v[16:19]
	v_mfma_f32_16x16x32_bf16 v[60:63], v[154:157], v[186:189], v[60:63]
	v_mfma_f32_16x16x32_bf16 v[56:59], v[158:161], v[186:189], v[56:59]
	v_mfma_f32_16x16x32_bf16 v[52:55], v[154:157], v[190:193], v[52:55]
	v_mfma_f32_16x16x32_bf16 v[48:51], v[158:161], v[190:193], v[48:51]
	s_waitcnt lgkmcnt(1)
	v_mfma_f32_16x16x32_bf16 v[36:39], v[154:157], v[202:205], v[36:39]
	v_mfma_f32_16x16x32_bf16 v[32:35], v[158:161], v[202:205], v[32:35]
	s_waitcnt lgkmcnt(0)
	v_mfma_f32_16x16x32_bf16 v[20:23], v[154:157], v[206:209], v[20:23]
	v_mfma_f32_16x16x32_bf16 v[16:19], v[158:161], v[206:209], v[16:19]
	s_setprio 0
	s_setprio 1
	v_mfma_f32_16x16x32_bf16 v[44:47], v[162:165], v[178:181], v[44:47]
	v_mfma_f32_16x16x32_bf16 v[40:43], v[166:169], v[178:181], v[40:43]
	v_mfma_f32_16x16x32_bf16 v[28:31], v[162:165], v[182:185], v[28:31]
	v_mfma_f32_16x16x32_bf16 v[24:27], v[166:169], v[182:185], v[24:27]
	v_mfma_f32_16x16x32_bf16 v[12:15], v[162:165], v[194:197], v[12:15]
	v_mfma_f32_16x16x32_bf16 v[8:11], v[166:169], v[194:197], v[8:11]
	v_mfma_f32_16x16x32_bf16 v[4:7], v[162:165], v[198:201], v[4:7]
	v_mfma_f32_16x16x32_bf16 v[0:3], v[166:169], v[198:201], v[0:3]
	v_mfma_f32_16x16x32_bf16 v[44:47], v[170:173], v[186:189], v[44:47]
	v_mfma_f32_16x16x32_bf16 v[40:43], v[174:177], v[186:189], v[40:43]
	v_mfma_f32_16x16x32_bf16 v[28:31], v[170:173], v[190:193], v[28:31]
	v_mfma_f32_16x16x32_bf16 v[24:27], v[174:177], v[190:193], v[24:27]
	v_mfma_f32_16x16x32_bf16 v[12:15], v[170:173], v[202:205], v[12:15]
	v_mfma_f32_16x16x32_bf16 v[8:11], v[174:177], v[202:205], v[8:11]
	v_mfma_f32_16x16x32_bf16 v[4:7], v[170:173], v[206:209], v[4:7]
	v_mfma_f32_16x16x32_bf16 v[0:3], v[174:177], v[206:209], v[0:3]
	s_setprio 0
	s_barrier
	s_add_i32 s76, s76, 2
	s_addk_i32 s73, 0x100
	s_addk_i32 s75, 0x100
	s_cmp_gt_u32 s76, 61
	s_cbranch_scc0 .LBB0_513
	s_and_b64 vcc, exec, s[20:21]
	s_cbranch_vccz .LBB0_516
	s_barrier

; #define LAS __attribute__((address_space(3)))
; __device__ __forceinline__ int lane_id() { int l; asm volatile("v_mbcnt_lo_u32_b32 %0, -1, 0\n\tv_mbcnt_hi_u32_b32 %0, -1, %0" : "=v"(l)); return l; }
; __global__ void __launch_bounds__(NTHREADS, 2) enc_fwd(Args args) {
;     extern __shared__ __attribute__((aligned(16))) unsigned char lds_raw[];
;     Frame F;
;     F.lds = (LAS unsigned char*)lds_raw;
;     F.wave = __builtin_amdgcn_readfirstlane(threadIdx.x >> 6); F.tid = F.wave * 64 + lane_id(); F.lane = F.tid & 63;
	.amdhsa_kernel _Z7enc_fwd4Args
		.amdhsa_group_segment_fixed_size 0
		.amdhsa_private_segment_fixed_size 0
		.amdhsa_kernarg_size 384
		.amdhsa_user_sgpr_count 2
		.amdhsa_user_sgpr_dispatch_ptr 0
		.amdhsa_user_sgpr_queue_ptr 0
		.amdhsa_user_sgpr_kernarg_segment_ptr 1
		.amdhsa_user_sgpr_dispatch_id 0
		.amdhsa_user_sgpr_kernarg_preload_length 0
		.amdhsa_user_sgpr_kernarg_preload_offset 0
		.amdhsa_user_sgpr_private_segment_size 0
		.amdhsa_uses_dynamic_stack 0
		.amdhsa_enable_private_segment 0
		.amdhsa_system_sgpr_workgroup_id_x 1
		.amdhsa_system_sgpr_workgroup_id_y 0
		.amdhsa_system_sgpr_workgroup_id_z 0
		.amdhsa_system_sgpr_workgroup_info 0
		.amdhsa_system_vgpr_workitem_id 0
		.amdhsa_next_free_vgpr 256
		.amdhsa_next_free_sgpr 102
		.amdhsa_accum_offset 256
		.amdhsa_reserve_vcc 1
		.amdhsa_float_round_mode_32 0
		.amdhsa_float_round_mode_16_64 0
		.amdhsa_float_denorm_mode_32 3
		.amdhsa_float_denorm_mode_16_64 3
		.amdhsa_dx10_clamp 1
		.amdhsa_ieee_mode 1
		.amdhsa_fp16_overflow 0
		.amdhsa_tg_split 0
		.amdhsa_exception_fp_ieee_invalid_op 0
		.amdhsa_exception_fp_denorm_src 0
		.amdhsa_exception_fp_ieee_div_zero 0
		.amdhsa_exception_fp_ieee_overflow 0
		.amdhsa_exception_fp_ieee_underflow 0
		.amdhsa_exception_fp_ieee_inexact 0
		.amdhsa_exception_int_div_zero 0
	.end_amdhsa_kernel

; __global__ void __launch_bounds__(NTHREADS, 2) enc_fwd(Args args) {
amdhsa.kernels:
  - .agpr_count:     0
    .args:
      - .offset:         0
        .size:           128
        .value_kind:     by_value
      - .offset:         128
        .size:           4
        .value_kind:     hidden_block_count_x
      - .offset:         132
        .size:           4
        .value_kind:     hidden_block_count_y
      - .offset:         136
        .size:           4
        .value_kind:     hidden_block_count_z
      - .offset:         140
        .size:           2
        .value_kind:     hidden_group_size_x
      - .offset:         142
        .size:           2
        .value_kind:     hidden_group_size_y
      - .offset:         144
        .size:           2
        .value_kind:     hidden_group_size_z
      - .offset:         146
        .size:           2
        .value_kind:     hidden_remainder_x
      - .offset:         148
        .size:           2
        .value_kind:     hidden_remainder_y
      - .offset:         150
        .size:           2
        .value_kind:     hidden_remainder_z
      - .offset:         168
        .size:           8
        .value_kind:     hidden_global_offset_x
      - .offset:         176
        .size:           8
        .value_kind:     hidden_global_offset_y
      - .offset:         184
        .size:           8
        .value_kind:     hidden_global_offset_z
      - .offset:         192
        .size:           2
        .value_kind:     hidden_grid_dims
      - .offset:         248
        .size:           4
        .value_kind:     hidden_dynamic_lds_size
    .group_segment_fixed_size: 0
    .kernarg_segment_align: 8
    .kernarg_segment_size: 384
    .language:       OpenCL C
    .language_version:
      - 2
      - 0
    .max_flat_workgroup_size: 512
    .name:           _Z7enc_fwd4Args
    .private_segment_fixed_size: 0
    .sgpr_count:     108
    .sgpr_spill_count: 31
    .symbol:         _Z7enc_fwd4Args.kd
    .uniform_work_group_size: 1
    .uses_dynamic_stack: false
    .vgpr_count:     256
    .vgpr_spill_count: 0
    .wavefront_size: 64
